# FF2 K-loop: the last iteration no longer issues the 14 tile loads nobody reads (explicit waits keep the needed tiles ordered)
# speedup vs baseline: 1.0036x; 1.0009x over previous
.LBB0_615:
	v_add_u32_e32 v151, s51, v149
	ds_read_b128 v[152:155], v151
	ds_read_b128 v[156:159], v151 offset:1024
	ds_read_b128 v[160:163], v151 offset:2048
	ds_read_b128 v[164:167], v151 offset:3072
	v_add_u32_e32 v151, s56, v149
	ds_read_b128 v[168:171], v151
	ds_read_b128 v[172:175], v151 offset:1024
	ds_read_b128 v[176:179], v151 offset:2048
	ds_read_b128 v[180:183], v151 offset:3072
	s_add_u32 s38, s12, s36
	s_addc_u32 s39, s13, s37
	s_cmp_eq_u32 s63, 60
	s_cselect_b32 s42, s59, s38
	s_cselect_b32 s43, s23, s39
	s_cselect_b32 s40, s60, s61
	s_cselect_b32 s41, s21, s62
	s_add_u32 s38, s42, 0x8000
	s_addc_u32 s39, s43, 0
	s_add_i32 m0, s44, 0xc000
	ds_read_b128 v[184:187], v150
	ds_read_b128 v[188:191], v150 offset:1024
	ds_read_b128 v[192:195], v150 offset:2048
	ds_read_b128 v[196:199], v150 offset:3072
	ds_read_b128 v[200:203], v150 offset:4096
	ds_read_b128 v[204:207], v150 offset:5120
	ds_read_b128 v[208:211], v150 offset:6144
	ds_read_b128 v[212:215], v150 offset:7168
	global_load_lds_dwordx4 v146, s[12:13]
	s_add_i32 m0, s44, 0xe000
	s_nop 0
	global_load_lds_dwordx4 v144, s[12:13]
	s_waitcnt vmcnt(8)
	s_waitcnt lgkmcnt(0)
	s_setprio 1
	s_barrier
	v_mfma_f32_16x16x32_bf16 v[124:127], v[152:155], v[184:187], v[124:127]
	v_mfma_f32_16x16x32_bf16 v[120:123], v[160:163], v[184:187], v[120:123]
	v_mfma_f32_16x16x32_bf16 v[108:111], v[152:155], v[192:195], v[108:111]
	v_mfma_f32_16x16x32_bf16 v[104:107], v[160:163], v[192:195], v[104:107]
	v_mfma_f32_16x16x32_bf16 v[92:95], v[152:155], v[200:203], v[92:95]
	v_mfma_f32_16x16x32_bf16 v[88:91], v[160:163], v[200:203], v[88:91]
	v_mfma_f32_16x16x32_bf16 v[76:79], v[152:155], v[208:211], v[76:79]
	v_mfma_f32_16x16x32_bf16 v[72:75], v[160:163], v[208:211], v[72:75]
	v_mfma_f32_16x16x32_bf16 v[124:127], v[156:159], v[188:191], v[124:127]
	v_mfma_f32_16x16x32_bf16 v[120:123], v[164:167], v[188:191], v[120:123]
	v_mfma_f32_16x16x32_bf16 v[108:111], v[156:159], v[196:199], v[108:111]
	v_mfma_f32_16x16x32_bf16 v[104:107], v[164:167], v[196:199], v[104:107]
	v_mfma_f32_16x16x32_bf16 v[92:95], v[156:159], v[204:207], v[92:95]
	v_mfma_f32_16x16x32_bf16 v[88:91], v[164:167], v[204:207], v[88:91]
	v_mfma_f32_16x16x32_bf16 v[76:79], v[156:159], v[212:215], v[76:79]
	v_mfma_f32_16x16x32_bf16 v[72:75], v[164:167], v[212:215], v[72:75]
	v_mfma_f32_16x16x32_bf16 v[116:119], v[168:171], v[184:187], v[116:119]
	v_mfma_f32_16x16x32_bf16 v[112:115], v[176:179], v[184:187], v[112:115]
	v_mfma_f32_16x16x32_bf16 v[100:103], v[168:171], v[192:195], v[100:103]
	v_mfma_f32_16x16x32_bf16 v[96:99], v[176:179], v[192:195], v[96:99]
	v_mfma_f32_16x16x32_bf16 v[84:87], v[168:171], v[200:203], v[84:87]
	v_mfma_f32_16x16x32_bf16 v[80:83], v[176:179], v[200:203], v[80:83]
	v_mfma_f32_16x16x32_bf16 v[68:71], v[168:171], v[208:211], v[68:71]
	v_mfma_f32_16x16x32_bf16 v[64:67], v[176:179], v[208:211], v[64:67]
	v_mfma_f32_16x16x32_bf16 v[116:119], v[172:175], v[188:191], v[116:119]
	v_mfma_f32_16x16x32_bf16 v[112:115], v[180:183], v[188:191], v[112:115]
	v_mfma_f32_16x16x32_bf16 v[100:103], v[172:175], v[196:199], v[100:103]
	v_mfma_f32_16x16x32_bf16 v[96:99], v[180:183], v[196:199], v[96:99]
	v_mfma_f32_16x16x32_bf16 v[84:87], v[172:175], v[204:207], v[84:87]
	v_mfma_f32_16x16x32_bf16 v[80:83], v[180:183], v[204:207], v[80:83]
	v_mfma_f32_16x16x32_bf16 v[68:71], v[172:175], v[212:215], v[68:71]
	v_mfma_f32_16x16x32_bf16 v[64:67], v[180:183], v[212:215], v[64:67]
	s_barrier
	s_setprio 0
	s_add_i32 s64, s51, s35
	s_mov_b32 m0, s64
	ds_read_b128 v[184:187], v150 offset:16384
	ds_read_b128 v[188:191], v150 offset:17408
	ds_read_b128 v[192:195], v150 offset:18432
	ds_read_b128 v[196:199], v150 offset:19456
	ds_read_b128 v[200:203], v150 offset:20480
	ds_read_b128 v[204:207], v150 offset:21504
	ds_read_b128 v[208:211], v150 offset:22528
	ds_read_b128 v[212:215], v150 offset:23552
	s_cmp_eq_u32 s63, 60
	s_cbranch_scc0 .Lff2_dma0
	s_waitcnt vmcnt(2)
	s_branch .Lff2_join0
.Lff2_dma0:
	global_load_lds_dwordx4 v130, s[40:41]
	s_add_i32 m0, s64, 0x2000
	s_add_u32 s64, s40, 0x100000
	v_lshl_add_u64 v[218:219], s[40:41], 0, v[134:135]
	s_addc_u32 s65, s41, 0
	s_add_i32 s66, s56, s35
	global_load_lds_dwordx4 v[218:219], off
	s_mov_b32 m0, s66
	s_nop 0
	global_load_lds_dwordx4 v130, s[64:65]
	s_add_i32 m0, s66, 0x2000
	s_nop 0
	global_load_lds_dwordx4 v134, s[64:65]
	s_mov_b32 m0, s44
	s_nop 0
	global_load_lds_dwordx4 v128, s[42:43]
	s_mov_b32 m0, s45
	s_nop 0
	global_load_lds_dwordx4 v132, s[42:43]
.Lff2_join0:
	s_waitcnt vmcnt(8)
	s_waitcnt lgkmcnt(0)
	s_setprio 1
	s_barrier
	v_mfma_f32_16x16x32_bf16 v[60:63], v[152:155], v[184:187], v[60:63]
	v_mfma_f32_16x16x32_bf16 v[56:59], v[160:163], v[184:187], v[56:59]
	v_mfma_f32_16x16x32_bf16 v[44:47], v[152:155], v[192:195], v[44:47]
	v_mfma_f32_16x16x32_bf16 v[40:43], v[160:163], v[192:195], v[40:43]
	v_mfma_f32_16x16x32_bf16 v[28:31], v[152:155], v[200:203], v[28:31]
	v_mfma_f32_16x16x32_bf16 v[24:27], v[160:163], v[200:203], v[24:27]
	v_mfma_f32_16x16x32_bf16 v[12:15], v[152:155], v[208:211], v[12:15]
	v_mfma_f32_16x16x32_bf16 v[8:11], v[160:163], v[208:211], v[8:11]
	v_mfma_f32_16x16x32_bf16 v[60:63], v[156:159], v[188:191], v[60:63]
	v_mfma_f32_16x16x32_bf16 v[56:59], v[164:167], v[188:191], v[56:59]
	v_mfma_f32_16x16x32_bf16 v[44:47], v[156:159], v[196:199], v[44:47]
	v_mfma_f32_16x16x32_bf16 v[40:43], v[164:167], v[196:199], v[40:43]
	v_mfma_f32_16x16x32_bf16 v[28:31], v[156:159], v[204:207], v[28:31]
	v_mfma_f32_16x16x32_bf16 v[24:27], v[164:167], v[204:207], v[24:27]
	v_mfma_f32_16x16x32_bf16 v[12:15], v[156:159], v[212:215], v[12:15]
	v_mfma_f32_16x16x32_bf16 v[8:11], v[164:167], v[212:215], v[8:11]
	v_mfma_f32_16x16x32_bf16 v[52:55], v[168:171], v[184:187], v[52:55]
	v_mfma_f32_16x16x32_bf16 v[48:51], v[176:179], v[184:187], v[48:51]
	v_mfma_f32_16x16x32_bf16 v[36:39], v[168:171], v[192:195], v[36:39]
	v_mfma_f32_16x16x32_bf16 v[32:35], v[176:179], v[192:195], v[32:35]
	v_mfma_f32_16x16x32_bf16 v[20:23], v[168:171], v[200:203], v[20:23]
	v_mfma_f32_16x16x32_bf16 v[16:19], v[176:179], v[200:203], v[16:19]
	v_mfma_f32_16x16x32_bf16 v[4:7], v[168:171], v[208:211], v[4:7]
	v_mfma_f32_16x16x32_bf16 v[0:3], v[176:179], v[208:211], v[0:3]
	v_mfma_f32_16x16x32_bf16 v[52:55], v[172:175], v[188:191], v[52:55]
	v_mfma_f32_16x16x32_bf16 v[48:51], v[180:183], v[188:191], v[48:51]
	v_mfma_f32_16x16x32_bf16 v[36:39], v[172:175], v[196:199], v[36:39]
	v_mfma_f32_16x16x32_bf16 v[32:35], v[180:183], v[196:199], v[32:35]
	v_mfma_f32_16x16x32_bf16 v[20:23], v[172:175], v[204:207], v[20:23]
	v_mfma_f32_16x16x32_bf16 v[16:19], v[180:183], v[204:207], v[16:19]
	v_mfma_f32_16x16x32_bf16 v[4:7], v[172:175], v[212:215], v[4:7]
	v_mfma_f32_16x16x32_bf16 v[0:3], v[180:183], v[212:215], v[0:3]
	s_barrier
	s_setprio 0
	s_add_i32 s64, 0, 0x18000
	v_add_u32_e32 v151, s64, v149
	s_add_i32 s65, 0, 0x1c000
	ds_read_b128 v[152:155], v151
	ds_read_b128 v[156:159], v151 offset:1024
	ds_read_b128 v[160:163], v151 offset:2048
	ds_read_b128 v[164:167], v151 offset:3072
	v_add_u32_e32 v151, s65, v149
	ds_read_b128 v[168:171], v151
	ds_read_b128 v[172:175], v151 offset:1024
	ds_read_b128 v[176:179], v151 offset:2048
	ds_read_b128 v[180:183], v151 offset:3072
	s_add_u32 s42, s42, 0x2000
	s_addc_u32 s43, s43, 0
	s_mov_b32 m0, s46
	ds_read_b128 v[184:187], v150 offset:32768
	ds_read_b128 v[188:191], v150 offset:33792
	ds_read_b128 v[192:195], v150 offset:34816
	ds_read_b128 v[196:199], v150 offset:35840
	ds_read_b128 v[200:203], v150 offset:36864
	ds_read_b128 v[204:207], v150 offset:37888
	ds_read_b128 v[208:211], v150 offset:38912
	ds_read_b128 v[212:215], v150 offset:39936
	s_cmp_eq_u32 s63, 60
	s_cbranch_scc0 .Lff2_dma1
	s_waitcnt vmcnt(0)
	s_branch .Lff2_join1
.Lff2_dma1:
	global_load_lds_dwordx4 v128, s[42:43]
	s_mov_b32 m0, s47
	s_nop 0
	global_load_lds_dwordx4 v132, s[42:43]
.Lff2_join1:
	s_waitcnt vmcnt(8)
	s_waitcnt lgkmcnt(0)
	s_setprio 1
	s_barrier
	v_mfma_f32_16x16x32_bf16 v[124:127], v[152:155], v[184:187], v[124:127]
	v_mfma_f32_16x16x32_bf16 v[120:123], v[160:163], v[184:187], v[120:123]
	v_mfma_f32_16x16x32_bf16 v[108:111], v[152:155], v[192:195], v[108:111]
	v_mfma_f32_16x16x32_bf16 v[104:107], v[160:163], v[192:195], v[104:107]
	v_mfma_f32_16x16x32_bf16 v[92:95], v[152:155], v[200:203], v[92:95]
	v_mfma_f32_16x16x32_bf16 v[88:91], v[160:163], v[200:203], v[88:91]
	v_mfma_f32_16x16x32_bf16 v[76:79], v[152:155], v[208:211], v[76:79]
	v_mfma_f32_16x16x32_bf16 v[72:75], v[160:163], v[208:211], v[72:75]
	v_mfma_f32_16x16x32_bf16 v[124:127], v[156:159], v[188:191], v[124:127]
	v_mfma_f32_16x16x32_bf16 v[120:123], v[164:167], v[188:191], v[120:123]
	v_mfma_f32_16x16x32_bf16 v[108:111], v[156:159], v[196:199], v[108:111]
	v_mfma_f32_16x16x32_bf16 v[104:107], v[164:167], v[196:199], v[104:107]
	v_mfma_f32_16x16x32_bf16 v[92:95], v[156:159], v[204:207], v[92:95]
	v_mfma_f32_16x16x32_bf16 v[88:91], v[164:167], v[204:207], v[88:91]
	v_mfma_f32_16x16x32_bf16 v[76:79], v[156:159], v[212:215], v[76:79]
	v_mfma_f32_16x16x32_bf16 v[72:75], v[164:167], v[212:215], v[72:75]
	v_mfma_f32_16x16x32_bf16 v[116:119], v[168:171], v[184:187], v[116:119]
	v_mfma_f32_16x16x32_bf16 v[112:115], v[176:179], v[184:187], v[112:115]
	v_mfma_f32_16x16x32_bf16 v[100:103], v[168:171], v[192:195], v[100:103]
	v_mfma_f32_16x16x32_bf16 v[96:99], v[176:179], v[192:195], v[96:99]
	v_mfma_f32_16x16x32_bf16 v[84:87], v[168:171], v[200:203], v[84:87]
	v_mfma_f32_16x16x32_bf16 v[80:83], v[176:179], v[200:203], v[80:83]
	v_mfma_f32_16x16x32_bf16 v[68:71], v[168:171], v[208:211], v[68:71]
	v_mfma_f32_16x16x32_bf16 v[64:67], v[176:179], v[208:211], v[64:67]
	v_mfma_f32_16x16x32_bf16 v[116:119], v[172:175], v[188:191], v[116:119]
	v_mfma_f32_16x16x32_bf16 v[112:115], v[180:183], v[188:191], v[112:115]
	v_mfma_f32_16x16x32_bf16 v[100:103], v[172:175], v[196:199], v[100:103]
	v_mfma_f32_16x16x32_bf16 v[96:99], v[180:183], v[196:199], v[96:99]
	v_mfma_f32_16x16x32_bf16 v[84:87], v[172:175], v[204:207], v[84:87]
	v_mfma_f32_16x16x32_bf16 v[80:83], v[180:183], v[204:207], v[80:83]
	v_mfma_f32_16x16x32_bf16 v[68:71], v[172:175], v[212:215], v[68:71]
	v_mfma_f32_16x16x32_bf16 v[64:67], v[180:183], v[212:215], v[64:67]
	s_barrier
	s_setprio 0
	s_add_u32 s98, s40, s16
	s_addc_u32 s99, s41, s17
	s_add_i32 s42, s64, s35
	s_mov_b32 m0, s42
	ds_read_b128 v[184:187], v150 offset:49152
	ds_read_b128 v[188:191], v150 offset:50176
	ds_read_b128 v[192:195], v150 offset:51200
	ds_read_b128 v[196:199], v150 offset:52224
	ds_read_b128 v[200:203], v150 offset:53248
	ds_read_b128 v[204:207], v150 offset:54272
	ds_read_b128 v[208:211], v150 offset:55296
	ds_read_b128 v[212:215], v150 offset:56320
	s_cmp_eq_u32 s63, 60
	s_cbranch_scc0 .Lff2_dma2
	s_branch .Lff2_join2
.Lff2_dma2:
	global_load_lds_dwordx4 v130, s[98:99]
	s_add_i32 m0, s42, 0x2000
	s_add_u32 s40, s40, 0x100080
	v_lshl_add_u64 v[216:217], v[218:219], 0, s[16:17]
	s_addc_u32 s41, s41, 0
	s_add_i32 s42, s65, s35
	global_load_lds_dwordx4 v[216:217], off
	s_mov_b32 m0, s42
	s_nop 0
	global_load_lds_dwordx4 v130, s[40:41]
	s_add_i32 m0, s42, 0x2000
	s_nop 0
	global_load_lds_dwordx4 v134, s[40:41]
	s_mov_b32 m0, s48
	s_nop 0
	global_load_lds_dwordx4 v128, s[38:39]
	s_mov_b32 m0, s49
	s_nop 0
	global_load_lds_dwordx4 v132, s[38:39]
.Lff2_join2:
	s_waitcnt vmcnt(8)
	s_waitcnt lgkmcnt(0)
	s_setprio 1
	s_barrier
	v_mfma_f32_16x16x32_bf16 v[60:63], v[152:155], v[184:187], v[60:63]
	v_mfma_f32_16x16x32_bf16 v[56:59], v[160:163], v[184:187], v[56:59]
	v_mfma_f32_16x16x32_bf16 v[44:47], v[152:155], v[192:195], v[44:47]
	v_mfma_f32_16x16x32_bf16 v[40:43], v[160:163], v[192:195], v[40:43]
	v_mfma_f32_16x16x32_bf16 v[28:31], v[152:155], v[200:203], v[28:31]
	v_mfma_f32_16x16x32_bf16 v[24:27], v[160:163], v[200:203], v[24:27]
	v_mfma_f32_16x16x32_bf16 v[12:15], v[152:155], v[208:211], v[12:15]
	v_mfma_f32_16x16x32_bf16 v[8:11], v[160:163], v[208:211], v[8:11]
	v_mfma_f32_16x16x32_bf16 v[60:63], v[156:159], v[188:191], v[60:63]
	v_mfma_f32_16x16x32_bf16 v[56:59], v[164:167], v[188:191], v[56:59]
	v_mfma_f32_16x16x32_bf16 v[44:47], v[156:159], v[196:199], v[44:47]
	v_mfma_f32_16x16x32_bf16 v[40:43], v[164:167], v[196:199], v[40:43]
	v_mfma_f32_16x16x32_bf16 v[28:31], v[156:159], v[204:207], v[28:31]
	v_mfma_f32_16x16x32_bf16 v[24:27], v[164:167], v[204:207], v[24:27]
	v_mfma_f32_16x16x32_bf16 v[12:15], v[156:159], v[212:215], v[12:15]
	v_mfma_f32_16x16x32_bf16 v[8:11], v[164:167], v[212:215], v[8:11]
	v_mfma_f32_16x16x32_bf16 v[52:55], v[168:171], v[184:187], v[52:55]
	v_mfma_f32_16x16x32_bf16 v[48:51], v[176:179], v[184:187], v[48:51]
	v_mfma_f32_16x16x32_bf16 v[36:39], v[168:171], v[192:195], v[36:39]
	v_mfma_f32_16x16x32_bf16 v[32:35], v[176:179], v[192:195], v[32:35]
	v_mfma_f32_16x16x32_bf16 v[20:23], v[168:171], v[200:203], v[20:23]
	v_mfma_f32_16x16x32_bf16 v[16:19], v[176:179], v[200:203], v[16:19]
	v_mfma_f32_16x16x32_bf16 v[4:7], v[168:171], v[208:211], v[4:7]
	v_mfma_f32_16x16x32_bf16 v[0:3], v[176:179], v[208:211], v[0:3]
	v_mfma_f32_16x16x32_bf16 v[52:55], v[172:175], v[188:191], v[52:55]
	v_mfma_f32_16x16x32_bf16 v[48:51], v[180:183], v[188:191], v[48:51]
	v_mfma_f32_16x16x32_bf16 v[36:39], v[172:175], v[196:199], v[36:39]
	v_mfma_f32_16x16x32_bf16 v[32:35], v[180:183], v[196:199], v[32:35]
	v_mfma_f32_16x16x32_bf16 v[20:23], v[172:175], v[204:207], v[20:23]
	v_mfma_f32_16x16x32_bf16 v[16:19], v[180:183], v[204:207], v[16:19]
	v_mfma_f32_16x16x32_bf16 v[4:7], v[172:175], v[212:215], v[4:7]
	v_mfma_f32_16x16x32_bf16 v[0:3], v[180:183], v[212:215], v[0:3]
	s_barrier
	s_setprio 0
	s_add_i32 s63, s63, 2
	s_add_u32 s61, s61, 0x100
	s_addc_u32 s62, s62, 0
	s_add_u32 s36, s36, 0x10000
	s_addc_u32 s37, s37, 0
	v_lshl_add_u64 v[146:147], v[146:147], 0, s[18:19]
	s_cmp_gt_u32 s63, 61
	v_lshl_add_u64 v[144:145], v[144:145], 0, s[18:19]
	s_cbranch_scc0 .LBB0_615
	s_andn2_b64 vcc, exec, s[4:5]
	s_cbranch_vccnz .LBB0_607
	v_mov_b32_e32 v0, 0
	s_mov_b32 s8, s20
	s_mov_b32 s6, s22
	s_mov_b64 s[10:11], s[28:29]
	s_mov_b64 s[12:13], s[26:27]
	s_mov_b32 s50, s57
	v_mov_b32_e32 v1, v0
	v_mov_b32_e32 v2, v0
	v_mov_b32_e32 v3, v0
	v_mov_b32_e32 v4, v0
	v_mov_b32_e32 v5, v0
	v_mov_b32_e32 v6, v0
	v_mov_b32_e32 v7, v0
	v_mov_b32_e32 v16, v0
	v_mov_b32_e32 v17, v0
	v_mov_b32_e32 v18, v0
	v_mov_b32_e32 v19, v0
	v_mov_b32_e32 v20, v0
	v_mov_b32_e32 v21, v0
	v_mov_b32_e32 v22, v0
	v_mov_b32_e32 v23, v0
	v_mov_b32_e32 v32, v0
	v_mov_b32_e32 v33, v0
	v_mov_b32_e32 v34, v0
	v_mov_b32_e32 v35, v0
	v_mov_b32_e32 v36, v0
	v_mov_b32_e32 v37, v0
	v_mov_b32_e32 v38, v0
	v_mov_b32_e32 v39, v0
	v_mov_b32_e32 v48, v0
	v_mov_b32_e32 v49, v0
	v_mov_b32_e32 v50, v0
	v_mov_b32_e32 v51, v0
	v_mov_b32_e32 v52, v0
	v_mov_b32_e32 v53, v0
	v_mov_b32_e32 v54, v0
	v_mov_b32_e32 v55, v0
	v_mov_b32_e32 v8, v0
	v_mov_b32_e32 v9, v0
	v_mov_b32_e32 v10, v0
	v_mov_b32_e32 v11, v0
	v_mov_b32_e32 v12, v0
	v_mov_b32_e32 v13, v0
	v_mov_b32_e32 v14, v0
	v_mov_b32_e32 v15, v0
	v_mov_b32_e32 v24, v0
	v_mov_b32_e32 v25, v0
	v_mov_b32_e32 v26, v0
	v_mov_b32_e32 v27, v0
	v_mov_b32_e32 v28, v0
	v_mov_b32_e32 v29, v0
	v_mov_b32_e32 v30, v0
	v_mov_b32_e32 v31, v0
	v_mov_b32_e32 v40, v0
	v_mov_b32_e32 v41, v0
	v_mov_b32_e32 v42, v0
	v_mov_b32_e32 v43, v0
	v_mov_b32_e32 v44, v0
	v_mov_b32_e32 v45, v0
	v_mov_b32_e32 v46, v0
	v_mov_b32_e32 v47, v0
	v_mov_b32_e32 v56, v0
	v_mov_b32_e32 v57, v0
	v_mov_b32_e32 v58, v0
	v_mov_b32_e32 v59, v0
	v_mov_b32_e32 v60, v0
	v_mov_b32_e32 v61, v0
	v_mov_b32_e32 v62, v0
	v_mov_b32_e32 v63, v0
	v_mov_b32_e32 v64, v0
	v_mov_b32_e32 v65, v0
	v_mov_b32_e32 v66, v0
	v_mov_b32_e32 v67, v0
	v_mov_b32_e32 v68, v0
	v_mov_b32_e32 v69, v0
	v_mov_b32_e32 v70, v0
	v_mov_b32_e32 v71, v0
	v_mov_b32_e32 v80, v0
	v_mov_b32_e32 v81, v0
	v_mov_b32_e32 v82, v0
	v_mov_b32_e32 v83, v0
	v_mov_b32_e32 v84, v0
	v_mov_b32_e32 v85, v0
	v_mov_b32_e32 v86, v0
	v_mov_b32_e32 v87, v0
	v_mov_b32_e32 v96, v0
	v_mov_b32_e32 v97, v0
	v_mov_b32_e32 v98, v0
	v_mov_b32_e32 v99, v0
	v_mov_b32_e32 v100, v0
	v_mov_b32_e32 v101, v0
	v_mov_b32_e32 v102, v0
	v_mov_b32_e32 v103, v0
	v_mov_b32_e32 v112, v0
	v_mov_b32_e32 v113, v0
	v_mov_b32_e32 v114, v0
	v_mov_b32_e32 v115, v0
	v_mov_b32_e32 v116, v0
	v_mov_b32_e32 v117, v0
	v_mov_b32_e32 v118, v0
	v_mov_b32_e32 v119, v0
	v_mov_b32_e32 v72, v0
	v_mov_b32_e32 v73, v0
	v_mov_b32_e32 v74, v0
	v_mov_b32_e32 v75, v0
	v_mov_b32_e32 v76, v0
	v_mov_b32_e32 v77, v0
	v_mov_b32_e32 v78, v0
	v_mov_b32_e32 v79, v0
	v_mov_b32_e32 v88, v0
	v_mov_b32_e32 v89, v0
	v_mov_b32_e32 v90, v0
	v_mov_b32_e32 v91, v0
	v_mov_b32_e32 v92, v0
	v_mov_b32_e32 v93, v0
	v_mov_b32_e32 v94, v0
	v_mov_b32_e32 v95, v0
	v_mov_b32_e32 v104, v0
	v_mov_b32_e32 v105, v0
	v_mov_b32_e32 v106, v0
	v_mov_b32_e32 v107, v0
	v_mov_b32_e32 v108, v0
	v_mov_b32_e32 v109, v0
	v_mov_b32_e32 v110, v0
	v_mov_b32_e32 v111, v0
	v_mov_b32_e32 v120, v0
	v_mov_b32_e32 v121, v0
	v_mov_b32_e32 v122, v0
	v_mov_b32_e32 v123, v0
	v_mov_b32_e32 v124, v0
	v_mov_b32_e32 v125, v0
	v_mov_b32_e32 v126, v0
	v_mov_b32_e32 v127, v0
	s_branch .LBB0_607
